# GU SwiGLU epilogue: row-scale square folded into the sigmoid denominator (fma m*e+m, one packed multiply fewer per pair)
# baseline (speedup 1.0000x reference)
.LBB0_1106:
	s_lshl_b32 s0, s29, 8
	s_add_i32 s0, s0, s77
	v_and_or_b32 v160, v193, 15, s0
	v_bfe_u32 v180, v193, 4, 2
	v_add_f32_e32 v130, v195, v194
	v_add_f32_e32 v146, v196, v197
	v_add_f32_e32 v131, v199, v198
	v_add_f32_e32 v147, v200, v201
	v_add_f32_e32 v132, v203, v202
	v_add_f32_e32 v148, v204, v205
	v_add_f32_e32 v133, v207, v206
	v_add_f32_e32 v149, v208, v209
	v_add_f32_e32 v130, v130, v146
	v_add_f32_e32 v131, v131, v147
	v_add_f32_e32 v132, v132, v148
	v_add_f32_e32 v133, v133, v149
	ds_swizzle_b32 v146, v221 offset:swizzle(SWAP,16)
	ds_swizzle_b32 v147, v222 offset:swizzle(SWAP,16)
	ds_swizzle_b32 v148, v223 offset:swizzle(SWAP,16)
	ds_swizzle_b32 v149, v224 offset:swizzle(SWAP,16)
	ds_swizzle_b32 v150, v130 offset:swizzle(SWAP,16)
	ds_swizzle_b32 v151, v131 offset:swizzle(SWAP,16)
	ds_swizzle_b32 v152, v132 offset:swizzle(SWAP,16)
	ds_swizzle_b32 v153, v133 offset:swizzle(SWAP,16)
	s_lshl_b32 s0, s28, 7
	v_lshl_or_b32 v218, v180, 3, s0
	v_or_b32_e32 v218, s78, v218
	v_mul_lo_u32 v161, v160, s70
	v_lshl_add_u32 v161, v218, 1, v161
	s_waitcnt lgkmcnt(0)
	v_add_f32_e32 v154, v221, v146
	v_add_f32_e32 v155, v222, v147
	v_add_f32_e32 v156, v223, v148
	v_add_f32_e32 v157, v224, v149
	v_add_f32_e32 v158, v130, v150
	v_add_f32_e32 v159, v131, v151
	v_add_f32_e32 v162, v132, v152
	v_add_f32_e32 v163, v133, v153
	v_mov_b32_e32 v164, v154
	v_mov_b32_e32 v165, v155
	v_mov_b32_e32 v166, v156
	v_mov_b32_e32 v167, v157
	v_mov_b32_e32 v168, v158
	v_mov_b32_e32 v169, v159
	v_mov_b32_e32 v170, v162
	v_mov_b32_e32 v171, v163
	v_permlane32_swap_b32_e32 v154, v164
	v_permlane32_swap_b32_e32 v155, v165
	v_permlane32_swap_b32_e32 v156, v166
	v_permlane32_swap_b32_e32 v157, v167
	v_permlane32_swap_b32_e32 v158, v168
	v_permlane32_swap_b32_e32 v159, v169
	v_permlane32_swap_b32_e32 v162, v170
	v_permlane32_swap_b32_e32 v163, v171
	v_add_f32_e32 v154, v154, v164
	v_add_f32_e32 v155, v155, v165
	v_add_f32_e32 v156, v156, v166
	v_add_f32_e32 v157, v157, v167
	v_add_f32_e32 v158, v158, v168
	v_add_f32_e32 v159, v159, v169
	v_add_f32_e32 v162, v162, v170
	v_add_f32_e32 v163, v163, v171
	v_fma_f32 v154, v154, s62, v192
	v_fma_f32 v155, v155, s62, v192
	v_fma_f32 v156, v156, s62, v192
	v_fma_f32 v157, v157, s62, v192
	v_fma_f32 v158, v158, s62, v192
	v_fma_f32 v159, v159, s62, v192
	v_fma_f32 v162, v162, s62, v192
	v_fma_f32 v163, v163, s62, v192
	v_mov_b32_e32 v173, v154
	v_mov_b32_e32 v175, v155
	v_mov_b32_e32 v177, v156
	v_mov_b32_e32 v183, v157
	v_mov_b32_e32 v185, v158
	v_mov_b32_e32 v187, v159
	v_mov_b32_e32 v189, v162
	v_mov_b32_e32 v191, v163
	v_rsq_f32_e32 v154, v154
	v_rsq_f32_e32 v155, v155
	v_rsq_f32_e32 v156, v156
	v_rsq_f32_e32 v157, v157
	v_rsq_f32_e32 v158, v158
	v_rsq_f32_e32 v159, v159
	v_rsq_f32_e32 v162, v162
	v_rsq_f32_e32 v163, v163
	v_mul_f32_e32 v172, 0xbfb8aa3b, v154
	v_mul_f32_e32 v174, 0xbfb8aa3b, v155
	v_mul_f32_e32 v176, 0xbfb8aa3b, v156
	v_mul_f32_e32 v182, 0xbfb8aa3b, v157
	v_mul_f32_e32 v184, 0xbfb8aa3b, v158
	v_mul_f32_e32 v186, 0xbfb8aa3b, v159
	v_mul_f32_e32 v188, 0xbfb8aa3b, v162
	v_mul_f32_e32 v190, 0xbfb8aa3b, v163
	v_pk_mul_f32 v[228:229], v[122:123], v[172:173] op_sel_hi:[1,0]
	v_pk_mul_f32 v[230:231], v[124:125], v[172:173] op_sel_hi:[1,0]
	v_pk_mul_f32 v[232:233], v[114:115], v[172:173] op_sel_hi:[1,0]
	v_pk_mul_f32 v[234:235], v[116:117], v[172:173] op_sel_hi:[1,0]
	v_pk_mul_f32 v[236:237], v[106:107], v[174:175] op_sel_hi:[1,0]
	v_pk_mul_f32 v[238:239], v[108:109], v[174:175] op_sel_hi:[1,0]
	v_pk_mul_f32 v[240:241], v[98:99], v[174:175] op_sel_hi:[1,0]
	v_pk_mul_f32 v[242:243], v[100:101], v[174:175] op_sel_hi:[1,0]
	v_exp_f32_e32 v228, v228
	v_exp_f32_e32 v229, v229
	v_exp_f32_e32 v230, v230
	v_exp_f32_e32 v231, v231
	v_exp_f32_e32 v232, v232
	v_exp_f32_e32 v233, v233
	v_exp_f32_e32 v234, v234
	v_exp_f32_e32 v235, v235
	v_exp_f32_e32 v236, v236
	v_exp_f32_e32 v237, v237
	v_exp_f32_e32 v238, v238
	v_exp_f32_e32 v239, v239
	v_exp_f32_e32 v240, v240
	v_exp_f32_e32 v241, v241
	v_exp_f32_e32 v242, v242
	v_exp_f32_e32 v243, v243
	v_pk_fma_f32 v[228:229], v[228:229], v[172:173], v[172:173] op_sel:[0,1,1] op_sel_hi:[1,1,1]
	v_pk_fma_f32 v[230:231], v[230:231], v[172:173], v[172:173] op_sel:[0,1,1] op_sel_hi:[1,1,1]
	v_pk_fma_f32 v[232:233], v[232:233], v[172:173], v[172:173] op_sel:[0,1,1] op_sel_hi:[1,1,1]
	v_pk_fma_f32 v[234:235], v[234:235], v[172:173], v[172:173] op_sel:[0,1,1] op_sel_hi:[1,1,1]
	v_pk_fma_f32 v[236:237], v[236:237], v[174:175], v[174:175] op_sel:[0,1,1] op_sel_hi:[1,1,1]
	v_pk_fma_f32 v[238:239], v[238:239], v[174:175], v[174:175] op_sel:[0,1,1] op_sel_hi:[1,1,1]
	v_pk_fma_f32 v[240:241], v[240:241], v[174:175], v[174:175] op_sel:[0,1,1] op_sel_hi:[1,1,1]
	v_pk_fma_f32 v[242:243], v[242:243], v[174:175], v[174:175] op_sel:[0,1,1] op_sel_hi:[1,1,1]
	v_pk_mul_f32 v[122:123], v[122:123], v[126:127]
	v_pk_mul_f32 v[124:125], v[124:125], v[128:129]
	v_pk_mul_f32 v[114:115], v[114:115], v[118:119]
	v_pk_mul_f32 v[116:117], v[116:117], v[120:121]
	v_pk_mul_f32 v[106:107], v[106:107], v[110:111]
	v_pk_mul_f32 v[108:109], v[108:109], v[112:113]
	v_pk_mul_f32 v[98:99], v[98:99], v[102:103]
	v_pk_mul_f32 v[100:101], v[100:101], v[104:105]
	v_rcp_f32_e32 v228, v228
	v_rcp_f32_e32 v229, v229
	v_rcp_f32_e32 v230, v230
	v_rcp_f32_e32 v231, v231
	v_rcp_f32_e32 v232, v232
	v_rcp_f32_e32 v233, v233
	v_rcp_f32_e32 v234, v234
	v_rcp_f32_e32 v235, v235
	v_rcp_f32_e32 v236, v236
	v_rcp_f32_e32 v237, v237
	v_rcp_f32_e32 v238, v238
	v_rcp_f32_e32 v239, v239
	v_rcp_f32_e32 v240, v240
	v_rcp_f32_e32 v241, v241
	v_rcp_f32_e32 v242, v242
	v_rcp_f32_e32 v243, v243
	v_pk_mul_f32 v[228:229], v[122:123], v[228:229]
	v_pk_mul_f32 v[230:231], v[124:125], v[230:231]
	v_pk_mul_f32 v[232:233], v[114:115], v[232:233]
	v_pk_mul_f32 v[234:235], v[116:117], v[234:235]
	v_pk_mul_f32 v[236:237], v[106:107], v[236:237]
	v_pk_mul_f32 v[238:239], v[108:109], v[238:239]
	v_pk_mul_f32 v[240:241], v[98:99], v[240:241]
	v_pk_mul_f32 v[242:243], v[100:101], v[242:243]
	v_add_u32_e32 v218, 0x0, v161
	v_add_u32_e32 v219, 0x16000, v161
	v_cvt_pk_bf16_f32 v244, v228, v229
	v_cvt_pk_bf16_f32 v245, v230, v231
	v_cvt_pk_bf16_f32 v246, v232, v233
	v_cvt_pk_bf16_f32 v247, v234, v235
	v_cvt_pk_bf16_f32 v214, v236, v237
	v_cvt_pk_bf16_f32 v215, v238, v239
	v_cvt_pk_bf16_f32 v216, v240, v241
	v_cvt_pk_bf16_f32 v217, v242, v243
	global_store_dwordx4 v218, v[244:247], s[8:9]
	global_store_dwordx4 v219, v[214:217], s[8:9]
	v_pk_mul_f32 v[228:229], v[90:91], v[176:177] op_sel_hi:[1,0]
	v_pk_mul_f32 v[230:231], v[92:93], v[176:177] op_sel_hi:[1,0]
	v_pk_mul_f32 v[232:233], v[82:83], v[176:177] op_sel_hi:[1,0]
	v_pk_mul_f32 v[234:235], v[84:85], v[176:177] op_sel_hi:[1,0]
	v_pk_mul_f32 v[236:237], v[74:75], v[182:183] op_sel_hi:[1,0]
	v_pk_mul_f32 v[238:239], v[76:77], v[182:183] op_sel_hi:[1,0]
	v_pk_mul_f32 v[240:241], v[66:67], v[182:183] op_sel_hi:[1,0]
	v_pk_mul_f32 v[242:243], v[68:69], v[182:183] op_sel_hi:[1,0]
	v_exp_f32_e32 v228, v228
	v_exp_f32_e32 v229, v229
	v_exp_f32_e32 v230, v230
	v_exp_f32_e32 v231, v231
	v_exp_f32_e32 v232, v232
	v_exp_f32_e32 v233, v233
	v_exp_f32_e32 v234, v234
	v_exp_f32_e32 v235, v235
	v_exp_f32_e32 v236, v236
	v_exp_f32_e32 v237, v237
	v_exp_f32_e32 v238, v238
	v_exp_f32_e32 v239, v239
	v_exp_f32_e32 v240, v240
	v_exp_f32_e32 v241, v241
	v_exp_f32_e32 v242, v242
	v_exp_f32_e32 v243, v243
	v_pk_fma_f32 v[228:229], v[228:229], v[176:177], v[176:177] op_sel:[0,1,1] op_sel_hi:[1,1,1]
	v_pk_fma_f32 v[230:231], v[230:231], v[176:177], v[176:177] op_sel:[0,1,1] op_sel_hi:[1,1,1]
	v_pk_fma_f32 v[232:233], v[232:233], v[176:177], v[176:177] op_sel:[0,1,1] op_sel_hi:[1,1,1]
	v_pk_fma_f32 v[234:235], v[234:235], v[176:177], v[176:177] op_sel:[0,1,1] op_sel_hi:[1,1,1]
	v_pk_fma_f32 v[236:237], v[236:237], v[182:183], v[182:183] op_sel:[0,1,1] op_sel_hi:[1,1,1]
	v_pk_fma_f32 v[238:239], v[238:239], v[182:183], v[182:183] op_sel:[0,1,1] op_sel_hi:[1,1,1]
	v_pk_fma_f32 v[240:241], v[240:241], v[182:183], v[182:183] op_sel:[0,1,1] op_sel_hi:[1,1,1]
	v_pk_fma_f32 v[242:243], v[242:243], v[182:183], v[182:183] op_sel:[0,1,1] op_sel_hi:[1,1,1]
	v_pk_mul_f32 v[90:91], v[90:91], v[94:95]
	v_pk_mul_f32 v[92:93], v[92:93], v[96:97]
	v_pk_mul_f32 v[82:83], v[82:83], v[86:87]
	v_pk_mul_f32 v[84:85], v[84:85], v[88:89]
	v_pk_mul_f32 v[74:75], v[74:75], v[78:79]
	v_pk_mul_f32 v[76:77], v[76:77], v[80:81]
	v_pk_mul_f32 v[66:67], v[66:67], v[70:71]
	v_pk_mul_f32 v[68:69], v[68:69], v[72:73]
	v_rcp_f32_e32 v228, v228
	v_rcp_f32_e32 v229, v229
	v_rcp_f32_e32 v230, v230
	v_rcp_f32_e32 v231, v231
	v_rcp_f32_e32 v232, v232
	v_rcp_f32_e32 v233, v233
	v_rcp_f32_e32 v234, v234
	v_rcp_f32_e32 v235, v235
	v_rcp_f32_e32 v236, v236
	v_rcp_f32_e32 v237, v237
	v_rcp_f32_e32 v238, v238
	v_rcp_f32_e32 v239, v239
	v_rcp_f32_e32 v240, v240
	v_rcp_f32_e32 v241, v241
	v_rcp_f32_e32 v242, v242
	v_rcp_f32_e32 v243, v243
	v_pk_mul_f32 v[228:229], v[90:91], v[228:229]
	v_pk_mul_f32 v[230:231], v[92:93], v[230:231]
	v_pk_mul_f32 v[232:233], v[82:83], v[232:233]
	v_pk_mul_f32 v[234:235], v[84:85], v[234:235]
	v_pk_mul_f32 v[236:237], v[74:75], v[236:237]
	v_pk_mul_f32 v[238:239], v[76:77], v[238:239]
	v_pk_mul_f32 v[240:241], v[66:67], v[240:241]
	v_pk_mul_f32 v[242:243], v[68:69], v[242:243]
	v_add_u32_e32 v218, 0x2c000, v161
	v_add_u32_e32 v219, 0x42000, v161
	v_cvt_pk_bf16_f32 v244, v228, v229
	v_cvt_pk_bf16_f32 v245, v230, v231
	v_cvt_pk_bf16_f32 v246, v232, v233
	v_cvt_pk_bf16_f32 v247, v234, v235
	v_cvt_pk_bf16_f32 v214, v236, v237
	v_cvt_pk_bf16_f32 v215, v238, v239
	v_cvt_pk_bf16_f32 v216, v240, v241
	v_cvt_pk_bf16_f32 v217, v242, v243
	global_store_dwordx4 v218, v[244:247], s[8:9]
	global_store_dwordx4 v219, v[214:217], s[8:9]
	v_pk_mul_f32 v[228:229], v[58:59], v[184:185] op_sel_hi:[1,0]
	v_pk_mul_f32 v[230:231], v[60:61], v[184:185] op_sel_hi:[1,0]
	v_pk_mul_f32 v[232:233], v[50:51], v[184:185] op_sel_hi:[1,0]
	v_pk_mul_f32 v[234:235], v[52:53], v[184:185] op_sel_hi:[1,0]
	v_pk_mul_f32 v[236:237], v[42:43], v[186:187] op_sel_hi:[1,0]
	v_pk_mul_f32 v[238:239], v[44:45], v[186:187] op_sel_hi:[1,0]
	v_pk_mul_f32 v[240:241], v[34:35], v[186:187] op_sel_hi:[1,0]
	v_pk_mul_f32 v[242:243], v[36:37], v[186:187] op_sel_hi:[1,0]
	v_exp_f32_e32 v228, v228
	v_exp_f32_e32 v229, v229
	v_exp_f32_e32 v230, v230
	v_exp_f32_e32 v231, v231
	v_exp_f32_e32 v232, v232
	v_exp_f32_e32 v233, v233
	v_exp_f32_e32 v234, v234
	v_exp_f32_e32 v235, v235
	v_exp_f32_e32 v236, v236
	v_exp_f32_e32 v237, v237
	v_exp_f32_e32 v238, v238
	v_exp_f32_e32 v239, v239
	v_exp_f32_e32 v240, v240
	v_exp_f32_e32 v241, v241
	v_exp_f32_e32 v242, v242
	v_exp_f32_e32 v243, v243
	v_pk_fma_f32 v[228:229], v[228:229], v[184:185], v[184:185] op_sel:[0,1,1] op_sel_hi:[1,1,1]
	v_pk_fma_f32 v[230:231], v[230:231], v[184:185], v[184:185] op_sel:[0,1,1] op_sel_hi:[1,1,1]
	v_pk_fma_f32 v[232:233], v[232:233], v[184:185], v[184:185] op_sel:[0,1,1] op_sel_hi:[1,1,1]
	v_pk_fma_f32 v[234:235], v[234:235], v[184:185], v[184:185] op_sel:[0,1,1] op_sel_hi:[1,1,1]
	v_pk_fma_f32 v[236:237], v[236:237], v[186:187], v[186:187] op_sel:[0,1,1] op_sel_hi:[1,1,1]
	v_pk_fma_f32 v[238:239], v[238:239], v[186:187], v[186:187] op_sel:[0,1,1] op_sel_hi:[1,1,1]
	v_pk_fma_f32 v[240:241], v[240:241], v[186:187], v[186:187] op_sel:[0,1,1] op_sel_hi:[1,1,1]
	v_pk_fma_f32 v[242:243], v[242:243], v[186:187], v[186:187] op_sel:[0,1,1] op_sel_hi:[1,1,1]
	v_pk_mul_f32 v[58:59], v[58:59], v[62:63]
	v_pk_mul_f32 v[60:61], v[60:61], v[64:65]
	v_pk_mul_f32 v[50:51], v[50:51], v[54:55]
	v_pk_mul_f32 v[52:53], v[52:53], v[56:57]
	v_pk_mul_f32 v[42:43], v[42:43], v[46:47]
	v_pk_mul_f32 v[44:45], v[44:45], v[48:49]
	v_pk_mul_f32 v[34:35], v[34:35], v[38:39]
	v_pk_mul_f32 v[36:37], v[36:37], v[40:41]
	v_rcp_f32_e32 v228, v228
	v_rcp_f32_e32 v229, v229
	v_rcp_f32_e32 v230, v230
	v_rcp_f32_e32 v231, v231
	v_rcp_f32_e32 v232, v232
	v_rcp_f32_e32 v233, v233
	v_rcp_f32_e32 v234, v234
	v_rcp_f32_e32 v235, v235
	v_rcp_f32_e32 v236, v236
	v_rcp_f32_e32 v237, v237
	v_rcp_f32_e32 v238, v238
	v_rcp_f32_e32 v239, v239
	v_rcp_f32_e32 v240, v240
	v_rcp_f32_e32 v241, v241
	v_rcp_f32_e32 v242, v242
	v_rcp_f32_e32 v243, v243
	v_pk_mul_f32 v[228:229], v[58:59], v[228:229]
	v_pk_mul_f32 v[230:231], v[60:61], v[230:231]
	v_pk_mul_f32 v[232:233], v[50:51], v[232:233]
	v_pk_mul_f32 v[234:235], v[52:53], v[234:235]
	v_pk_mul_f32 v[236:237], v[42:43], v[236:237]
	v_pk_mul_f32 v[238:239], v[44:45], v[238:239]
	v_pk_mul_f32 v[240:241], v[34:35], v[240:241]
	v_pk_mul_f32 v[242:243], v[36:37], v[242:243]
	v_add_u32_e32 v218, 0xb0000, v161
	v_add_u32_e32 v219, 0xc6000, v161
	v_cvt_pk_bf16_f32 v244, v228, v229
	v_cvt_pk_bf16_f32 v245, v230, v231
	v_cvt_pk_bf16_f32 v246, v232, v233
	v_cvt_pk_bf16_f32 v247, v234, v235
	v_cvt_pk_bf16_f32 v214, v236, v237
	v_cvt_pk_bf16_f32 v215, v238, v239
	v_cvt_pk_bf16_f32 v216, v240, v241
	v_cvt_pk_bf16_f32 v217, v242, v243
	global_store_dwordx4 v218, v[244:247], s[8:9]
	global_store_dwordx4 v219, v[214:217], s[8:9]
	v_pk_mul_f32 v[228:229], v[26:27], v[188:189] op_sel_hi:[1,0]
	v_pk_mul_f32 v[230:231], v[28:29], v[188:189] op_sel_hi:[1,0]
	v_pk_mul_f32 v[232:233], v[18:19], v[188:189] op_sel_hi:[1,0]
	v_pk_mul_f32 v[234:235], v[20:21], v[188:189] op_sel_hi:[1,0]
	v_pk_mul_f32 v[236:237], v[10:11], v[190:191] op_sel_hi:[1,0]
	v_pk_mul_f32 v[238:239], v[12:13], v[190:191] op_sel_hi:[1,0]
	v_pk_mul_f32 v[240:241], v[6:7], v[190:191] op_sel_hi:[1,0]
	v_pk_mul_f32 v[242:243], v[8:9], v[190:191] op_sel_hi:[1,0]
	v_exp_f32_e32 v228, v228
	v_exp_f32_e32 v229, v229
	v_exp_f32_e32 v230, v230
	v_exp_f32_e32 v231, v231
	v_exp_f32_e32 v232, v232
	v_exp_f32_e32 v233, v233
	v_exp_f32_e32 v234, v234
	v_exp_f32_e32 v235, v235
	v_exp_f32_e32 v236, v236
	v_exp_f32_e32 v237, v237
	v_exp_f32_e32 v238, v238
	v_exp_f32_e32 v239, v239
	v_exp_f32_e32 v240, v240
	v_exp_f32_e32 v241, v241
	v_exp_f32_e32 v242, v242
	v_exp_f32_e32 v243, v243
	v_pk_fma_f32 v[228:229], v[228:229], v[188:189], v[188:189] op_sel:[0,1,1] op_sel_hi:[1,1,1]
	v_pk_fma_f32 v[230:231], v[230:231], v[188:189], v[188:189] op_sel:[0,1,1] op_sel_hi:[1,1,1]
	v_pk_fma_f32 v[232:233], v[232:233], v[188:189], v[188:189] op_sel:[0,1,1] op_sel_hi:[1,1,1]
	v_pk_fma_f32 v[234:235], v[234:235], v[188:189], v[188:189] op_sel:[0,1,1] op_sel_hi:[1,1,1]
	v_pk_fma_f32 v[236:237], v[236:237], v[190:191], v[190:191] op_sel:[0,1,1] op_sel_hi:[1,1,1]
	v_pk_fma_f32 v[238:239], v[238:239], v[190:191], v[190:191] op_sel:[0,1,1] op_sel_hi:[1,1,1]
	v_pk_fma_f32 v[240:241], v[240:241], v[190:191], v[190:191] op_sel:[0,1,1] op_sel_hi:[1,1,1]
	v_pk_fma_f32 v[242:243], v[242:243], v[190:191], v[190:191] op_sel:[0,1,1] op_sel_hi:[1,1,1]
	v_pk_mul_f32 v[26:27], v[26:27], v[30:31]
	v_pk_mul_f32 v[28:29], v[28:29], v[32:33]
	v_pk_mul_f32 v[18:19], v[18:19], v[22:23]
	v_pk_mul_f32 v[20:21], v[20:21], v[24:25]
	v_pk_mul_f32 v[10:11], v[10:11], v[14:15]
	v_pk_mul_f32 v[12:13], v[12:13], v[16:17]
	v_pk_mul_f32 v[6:7], v[6:7], v[2:3]
	v_pk_mul_f32 v[8:9], v[8:9], v[4:5]
	v_rcp_f32_e32 v228, v228
	v_rcp_f32_e32 v229, v229
	v_rcp_f32_e32 v230, v230
	v_rcp_f32_e32 v231, v231
	v_rcp_f32_e32 v232, v232
	v_rcp_f32_e32 v233, v233
	v_rcp_f32_e32 v234, v234
	v_rcp_f32_e32 v235, v235
	v_rcp_f32_e32 v236, v236
	v_rcp_f32_e32 v237, v237
	v_rcp_f32_e32 v238, v238
	v_rcp_f32_e32 v239, v239
	v_rcp_f32_e32 v240, v240
	v_rcp_f32_e32 v241, v241
	v_rcp_f32_e32 v242, v242
	v_rcp_f32_e32 v243, v243
	v_pk_mul_f32 v[228:229], v[26:27], v[228:229]
	v_pk_mul_f32 v[230:231], v[28:29], v[230:231]
	v_pk_mul_f32 v[232:233], v[18:19], v[232:233]
	v_pk_mul_f32 v[234:235], v[20:21], v[234:235]
	v_pk_mul_f32 v[236:237], v[10:11], v[236:237]
	v_pk_mul_f32 v[238:239], v[12:13], v[238:239]
	v_pk_mul_f32 v[240:241], v[6:7], v[240:241]
	v_pk_mul_f32 v[242:243], v[8:9], v[242:243]
	v_add_u32_e32 v218, 0xdc000, v161
	v_add_u32_e32 v219, 0xf2000, v161
	v_cvt_pk_bf16_f32 v244, v228, v229
	v_cvt_pk_bf16_f32 v245, v230, v231
	v_cvt_pk_bf16_f32 v246, v232, v233
	v_cvt_pk_bf16_f32 v247, v234, v235
	v_cvt_pk_bf16_f32 v214, v236, v237
	v_cvt_pk_bf16_f32 v215, v238, v239
	v_cvt_pk_bf16_f32 v216, v240, v241
	v_cvt_pk_bf16_f32 v217, v242, v243
	global_store_dwordx4 v218, v[244:247], s[8:9]
	global_store_dwordx4 v219, v[214:217], s[8:9]
	s_mov_b64 s[2:3], -1
	s_andn2_b64 vcc, exec, s[38:39]
	s_cbranch_vccnz .LBB0_1099
	s_andn2_b64 vcc, exec, s[6:7]
	s_cbranch_vccnz .LBB0_1098
	s_barrier
	s_branch .LBB0_1098
